# DSA/SWA item loops: next-item atomic no longer waited at item start (returns into the register consumed at item end)
# speedup vs baseline: 1.0299x; 1.0029x over previous
.LBB0_186:
	v_mov_b32_e32 v200, v151
	s_and_saveexec_b64 s[28:29], s[30:31]
	s_cbranch_execz .LBB0_190
	s_mov_b64 s[42:43], exec
	v_mbcnt_lo_u32_b32 v2, s42, 0
	v_mbcnt_hi_u32_b32 v2, s43, v2
	v_cmp_eq_u32_e32 vcc, 0, v2
	s_and_saveexec_b64 s[34:35], vcc
	s_cbranch_execz .LBB0_189
	s_bcnt1_i32_b64 s42, s[42:43]
	v_mov_b32_e32 v3, s42
	global_atomic_add v200, v151, v3, s[36:37] sc0
.LBB0_189:
	s_or_b64 exec, exec, s[34:35]
.LBB0_190:
	s_or_b64 exec, exec, s[28:29]
	s_lshl_b32 s29, s38, 3
	v_readfirstlane_b32 s28, v147
	s_sub_i32 s46, 0xff8, s29
	s_and_b64 vcc, exec, s[26:27]
	s_lshr_b32 s47, s28, 6
	s_cbranch_vccnz .LBB0_196
	s_sub_i32 s29, 0x1018, s29
	s_lshr_b32 s34, s29, 5
	s_cmp_ge_u32 s47, s34
	s_cbranch_scc1 .LBB0_196
	s_add_i32 s29, s46, s3
	v_or_b32_e32 v150, s29, v168
	v_lshlrev_b64 v[2:3], 10, v[150:151]
	v_lshl_add_u64 v[2:3], v[152:153], 0, v[2:3]
	v_add_co_u32_e32 v6, vcc, 0x1000, v2
	v_or_b32_e32 v150, s29, v170
	global_load_dwordx4 v[34:37], v[2:3], off
	global_load_dwordx4 v[38:41], v[2:3], off offset:32
	global_load_dwordx4 v[42:45], v[2:3], off offset:64
	global_load_dwordx4 v[46:49], v[2:3], off offset:96
	v_addc_co_u32_e32 v7, vcc, 0, v3, vcc
	v_lshlrev_b64 v[2:3], 5, v[150:151]
	v_lshl_add_u64 v[2:3], s[64:65], 0, v[2:3]
	global_load_dwordx4 v[50:53], v[6:7], off
	global_load_dwordx4 v[54:57], v[6:7], off offset:32
	global_load_dwordx4 v[58:61], v[2:3], off offset:48
	global_load_dwordx4 v[62:65], v[2:3], off offset:32
	global_load_dwordx4 v[66:69], v[2:3], off offset:16
	global_load_dwordx4 v[70:73], v[2:3], off
	global_load_dwordx4 v[74:77], v[2:3], off offset:176
	global_load_dwordx4 v[78:81], v[2:3], off offset:160
	global_load_dwordx4 v[82:85], v[2:3], off offset:144
	global_load_dwordx4 v[86:89], v[2:3], off offset:128
	s_lshl_b32 s38, s47, 5
	s_lshl_b64 s[42:43], s[38:39], 7
	v_lshl_add_u64 v[8:9], v[154:155], 0, s[42:43]
	global_load_dwordx4 v[118:121], v[8:9], off offset:64
	global_load_dwordx4 v[114:117], v[8:9], off offset:96
	global_load_dwordx4 v[2:5], v[8:9], off
	global_load_dwordx4 v[122:125], v[8:9], off offset:32
	global_load_dwordx4 v[90:93], v[6:7], off offset:64
	global_load_dwordx4 v[94:97], v[6:7], off offset:96
	s_lshl_b64 s[28:29], s[28:29], 6
	s_and_b32 s29, s29, 63
	s_and_b32 s28, s28, 0xfffff000
	v_or_b32_e32 v128, s46, v170
	v_or_b32_e32 v129, s46, v171
	v_or_b32_e32 v130, s46, v172
	v_or_b32_e32 v131, s46, v173
	v_lshl_add_u32 v132, s47, 6, v192
	s_mov_b32 s35, s47
	v_or_b32_e32 v133, s38, v149
	v_lshl_add_u64 v[126:127], v[164:165], 0, s[28:29]
	s_waitcnt vmcnt(5)
	v_mov_b64_e32 v[102:103], v[118:119]
	s_waitcnt vmcnt(4)
	v_mov_b64_e32 v[98:99], v[114:115]
	s_waitcnt vmcnt(3)
	v_mov_b64_e32 v[112:113], v[4:5]
	s_waitcnt vmcnt(2)
	v_mov_b64_e32 v[106:107], v[122:123]
	v_mov_b64_e32 v[100:101], v[116:117]
	v_mov_b64_e32 v[104:105], v[120:121]
	v_mov_b64_e32 v[108:109], v[124:125]
	v_mov_b64_e32 v[110:111], v[2:3]
	s_branch .LBB0_194

.LBB0_538:
	v_mov_b32_e32 v136, 0
	s_and_saveexec_b64 s[38:39], s[52:53]
	s_cbranch_execz .LBB0_542
	s_mov_b64 s[42:43], exec
	v_mbcnt_lo_u32_b32 v2, s42, 0
	v_mbcnt_hi_u32_b32 v2, s43, v2
	v_cmp_eq_u32_e32 vcc, 0, v2
	s_and_saveexec_b64 s[40:41], vcc
	s_cbranch_execz .LBB0_541
	s_bcnt1_i32_b64 s42, s[42:43]
	v_mov_b32_e32 v3, s42
	global_atomic_add v136, v95, v3, s[60:61] sc0
.LBB0_541:
	s_or_b64 exec, exec, s[40:41]
.LBB0_542:
	s_or_b64 exec, exec, s[38:39]
	s_and_b32 s38, s44, 1
	v_readfirstlane_b32 s39, v1
	s_ashr_i32 s49, s44, 1
	s_lshr_b32 s78, s39, 6
	s_lshl_b32 s39, s38, 2
	s_lshl_b32 s72, s49, 5
	s_add_i32 s78, s78, s39
	s_add_i32 s48, s72, 0xffffff80
	s_lshl_b32 s64, s38, 7
	s_ashr_i32 s73, s72, 31
	s_lshl_b32 s70, s78, 7
	s_cmp_gt_i32 s49, 3
	s_cselect_b64 s[44:45], -1, 0
	s_add_i32 s86, s72, 0xffffffa0
	s_cmp_gt_i32 s49, 2
	v_or_b32_e32 v6, s48, v116
	v_or_b32_e32 v10, s86, v116
	s_cselect_b64 s[42:43], -1, 0
	v_cndmask_b32_e64 v6, 0, v6, s[44:45]
	v_cndmask_b32_e64 v10, 0, v10, s[42:43]
	v_ashrrev_i32_e32 v7, 31, v6
	v_ashrrev_i32_e32 v11, 31, v10
	v_lshl_add_u64 v[2:3], s[72:73], 0, v[96:97]
	v_lshl_add_u64 v[6:7], v[6:7], 0, s[62:63]
	v_lshl_add_u64 v[10:11], v[10:11], 0, s[62:63]
	v_lshlrev_b64 v[2:3], 10, v[2:3]
	v_lshlrev_b64 v[6:7], 9, v[6:7]
	v_lshlrev_b64 v[10:11], 9, v[10:11]
	v_lshl_add_u64 v[2:3], s[66:67], 0, v[2:3]
	s_mov_b32 s71, s65
	v_lshl_add_u64 v[6:7], s[68:69], 0, v[6:7]
	v_lshl_add_u64 v[10:11], s[68:69], 0, v[10:11]
	v_lshl_add_u64 v[2:3], v[2:3], 0, s[70:71]
	v_lshl_add_u64 v[6:7], v[6:7], 0, s[64:65]
	v_lshl_add_u64 v[10:11], v[10:11], 0, s[64:65]
	v_lshl_add_u64 v[86:87], v[2:3], 0, v[102:103]
	v_lshl_add_u64 v[34:35], v[6:7], 0, v[102:103]
	v_lshl_add_u64 v[106:107], v[10:11], 0, v[102:103]
	s_barrier
	global_load_dwordx4 v[2:5], v[86:87], off
	global_load_dwordx4 v[6:9], v[34:35], off
	global_load_dwordx4 v[10:13], v[106:107], off
	s_sub_i32 s79, s72, 64
	s_cmp_gt_i32 s49, 1
	v_or_b32_e32 v14, s79, v116
	s_cselect_b64 s[40:41], -1, 0
	v_cndmask_b32_e64 v14, 0, v14, s[40:41]
	v_ashrrev_i32_e32 v15, 31, v14
	v_lshl_add_u64 v[14:15], v[14:15], 0, s[62:63]
	v_lshlrev_b64 v[14:15], 9, v[14:15]
	v_lshl_add_u64 v[14:15], s[68:69], 0, v[14:15]
	v_lshl_add_u64 v[14:15], v[14:15], 0, s[64:65]
	v_lshl_add_u64 v[142:143], v[14:15], 0, v[102:103]
	global_load_dwordx4 v[14:17], v[142:143], off
	global_load_dwordx4 v[18:21], v[34:35], off offset:32
	global_load_dwordx4 v[90:93], v[86:87], off offset:32
	global_load_dwordx4 v[22:25], v[106:107], off offset:32
	global_load_dwordx4 v[26:29], v[142:143], off offset:32
	global_load_dwordx4 v[30:33], v[34:35], off offset:64
	global_load_dwordx4 v[138:141], v[86:87], off offset:64
	s_sub_i32 s73, s72, 32
	s_cmp_gt_i32 s49, 0
	v_or_b32_e32 v94, s73, v116
	s_cselect_b64 s[38:39], -1, 0
	s_cmp_gt_i32 s49, -1
	s_cselect_b64 vcc, -1, 0
	s_load_dwordx16 s[4:19], s[0:1], 0x80
	s_waitcnt vmcnt(8)
	v_mfma_f32_32x32x16_bf16 v[66:81], v[6:9], v[2:5], 0
	global_load_dwordx4 v[6:9], v[106:107], off offset:64
	s_waitcnt vmcnt(8)
	v_mfma_f32_32x32x16_bf16 v[50:65], v[10:13], v[2:5], 0
	global_load_dwordx4 v[10:13], v[142:143], off offset:64
	global_load_dwordx4 v[82:85], v[34:35], off offset:96
	s_waitcnt vmcnt(9)
	v_mfma_f32_32x32x16_bf16 v[34:49], v[14:17], v[2:5], 0
	global_load_dwordx4 v[86:89], v[86:87], off offset:96
	s_nop 0
	global_load_dwordx4 v[14:17], v[106:107], off offset:96
	v_or_b32_e32 v106, s72, v116
	s_waitcnt vmcnt(7)
	v_mfma_f32_32x32x16_bf16 v[34:49], v[26:29], v[90:93], v[34:49]
	v_mfma_f32_32x32x16_bf16 v[66:81], v[18:21], v[90:93], v[66:81]
	v_cndmask_b32_e64 v18, 0, v94, s[38:39]
	v_ashrrev_i32_e32 v19, 31, v18
	v_lshl_add_u64 v[18:19], v[18:19], 0, s[62:63]
	v_lshlrev_b64 v[18:19], 9, v[18:19]
	v_lshl_add_u64 v[18:19], s[68:69], 0, v[18:19]
	v_lshl_add_u64 v[18:19], v[18:19], 0, s[64:65]
	v_lshl_add_u64 v[176:177], v[18:19], 0, v[102:103]
	v_mfma_f32_32x32x16_bf16 v[50:65], v[22:25], v[90:93], v[50:65]
	v_add_u32_e32 v22, s48, v147
	v_max_i32_e32 v22, 0, v22
	v_add_u32_e32 v23, s48, v109
	v_add_u32_e32 v94, s62, v22
	v_add_u32_e32 v24, s48, v111
	v_max_i32_e32 v26, 0, v23
	v_lshlrev_b64 v[22:23], 9, v[94:95]
	v_add_u32_e32 v25, s48, v113
	v_max_i32_e32 v27, 0, v24
	v_add_u32_e32 v94, s62, v26
	v_lshl_add_u64 v[22:23], s[68:69], 0, v[22:23]
	v_max_i32_e32 v28, 0, v25
	v_lshlrev_b64 v[24:25], 9, v[94:95]
	v_add_u32_e32 v94, s62, v27
	v_lshl_add_u64 v[22:23], v[22:23], 0, s[64:65]
	v_lshl_add_u64 v[24:25], s[68:69], 0, v[24:25]
	v_lshlrev_b64 v[26:27], 9, v[94:95]
	v_lshl_add_u64 v[22:23], v[22:23], 0, v[100:101]
	global_load_dwordx4 v[18:21], v[176:177], off
	s_nop 0
	global_load_dwordx4 v[142:145], v[142:143], off offset:96
	s_waitcnt vmcnt(5)
	v_mfma_f32_32x32x16_bf16 v[34:49], v[10:13], v[138:141], v[34:49]
	global_load_dwordx4 v[148:151], v[22:23], off offset:256
	global_load_dwordx4 v[10:13], v[176:177], off offset:64
	v_lshl_add_u64 v[22:23], v[24:25], 0, s[64:65]
	v_lshl_add_u64 v[24:25], s[68:69], 0, v[26:27]
	v_lshl_add_u64 v[22:23], v[22:23], 0, v[100:101]
	v_lshl_add_u64 v[24:25], v[24:25], 0, s[64:65]
	global_load_dwordx4 v[152:155], v[22:23], off offset:256
	v_lshl_add_u64 v[22:23], v[24:25], 0, v[100:101]
	global_load_dwordx4 v[156:159], v[22:23], off offset:256
	v_cndmask_b32_e32 v22, 0, v106, vcc
	v_ashrrev_i32_e32 v23, 31, v22
	v_lshl_add_u64 v[22:23], v[22:23], 0, s[62:63]
	v_lshlrev_b64 v[22:23], 9, v[22:23]
	v_mfma_f32_32x32x16_bf16 v[50:65], v[6:9], v[138:141], v[50:65]
	v_add_u32_e32 v94, s62, v28
	v_lshl_add_u64 v[22:23], s[68:69], 0, v[22:23]
	v_lshlrev_b64 v[26:27], 9, v[94:95]
	v_lshl_add_u64 v[22:23], v[22:23], 0, s[64:65]
	v_lshl_add_u64 v[180:181], v[22:23], 0, v[102:103]
	v_lshl_add_u64 v[22:23], s[68:69], 0, v[26:27]
	v_lshl_add_u64 v[22:23], v[22:23], 0, s[64:65]
	v_mfma_f32_32x32x16_bf16 v[66:81], v[30:33], v[138:141], v[66:81]
	v_lshl_add_u64 v[22:23], v[22:23], 0, v[100:101]
	global_load_dwordx4 v[160:163], v[180:181], off
	global_load_dwordx4 v[164:167], v[22:23], off offset:256
	v_add_u32_e32 v22, s48, v115
	v_max_i32_e32 v22, 0, v22
	v_add_u32_e32 v94, s62, v22
	global_load_dwordx4 v[6:9], v[176:177], off offset:32
	s_waitcnt vmcnt(9)
	v_mfma_f32_32x32x16_bf16 v[50:65], v[14:17], v[86:89], v[50:65]
	v_lshlrev_b64 v[14:15], 9, v[94:95]
	v_lshl_add_u64 v[14:15], s[68:69], 0, v[14:15]
	v_lshl_add_u64 v[14:15], v[14:15], 0, s[64:65]
	v_lshl_add_u64 v[14:15], v[14:15], 0, v[100:101]
	global_load_dwordx4 v[168:171], v[180:181], off offset:32
	v_mfma_f32_32x32x16_bf16 v[66:81], v[82:85], v[86:89], v[66:81]
	global_load_dwordx4 v[82:85], v[14:15], off offset:256
	global_load_dwordx4 v[172:175], v[180:181], off offset:64
	s_nop 0
	global_load_dwordx4 v[176:179], v[176:177], off offset:96
	s_waitcnt vmcnt(10)
	ds_write_b16 v108, v148
	ds_write_b16_d16_hi v108, v148 offset:336
	ds_write_b16 v108, v149 offset:672
	ds_write_b16_d16_hi v108, v149 offset:1008
	ds_write_b16 v108, v150 offset:1344
	ds_write_b16_d16_hi v108, v150 offset:1680
	ds_write_b16 v108, v151 offset:2016
	ds_write_b16_d16_hi v108, v151 offset:2352
	s_waitcnt vmcnt(8)
	ds_write_b16 v110, v152
	ds_write_b16_d16_hi v110, v152 offset:336
	ds_write_b16 v110, v153 offset:672
	ds_write_b16_d16_hi v110, v153 offset:1008
	ds_write_b16 v110, v154 offset:1344
	ds_write_b16_d16_hi v110, v154 offset:1680
	ds_write_b16 v110, v155 offset:2016
	ds_write_b16_d16_hi v110, v155 offset:2352
	s_waitcnt vmcnt(7)
	ds_write_b16 v112, v156
	ds_write_b16_d16_hi v112, v156 offset:336
	ds_write_b16 v112, v157 offset:672
	ds_write_b16_d16_hi v112, v157 offset:1008
	ds_write_b16 v112, v158 offset:1344
	ds_write_b16_d16_hi v112, v158 offset:1680
	ds_write_b16 v112, v159 offset:2016
	ds_write_b16_d16_hi v112, v159 offset:2352
	s_waitcnt vmcnt(5)
	ds_write_b16 v114, v164
	ds_write_b16_d16_hi v114, v164 offset:336
	ds_write_b16 v114, v165 offset:672
	ds_write_b16_d16_hi v114, v165 offset:1008
	ds_write_b16 v114, v166 offset:1344
	ds_write_b16_d16_hi v114, v166 offset:1680
	ds_write_b16 v114, v167 offset:2016
	ds_write_b16_d16_hi v114, v167 offset:2352
	s_waitcnt vmcnt(2)
	ds_write_b16 v108, v82 offset:256
	ds_write_b16_d16_hi v108, v82 offset:592
	ds_write_b16 v108, v83 offset:928
	ds_write_b16_d16_hi v108, v83 offset:1264
	v_or_b32_e32 v83, s48, v98
	v_add_u32_e32 v82, 0xffffff80, v106
	v_cmp_gt_i32_e64 s[50:51], v83, v82
	v_cmp_le_i32_e64 s[48:49], v83, v106
	s_and_b64 s[50:51], s[44:45], s[50:51]
	s_and_b64 s[48:49], s[50:51], s[48:49]
	v_cndmask_b32_e64 v66, v132, v66, s[48:49]
	v_cmp_lt_i32_e64 s[48:49], v83, v106
	s_and_b64 s[50:51], s[44:45], s[48:49]
	v_cmp_ge_i32_e64 s[48:49], v83, v82
	v_or_b32_e32 v107, 2, v83
	s_and_b64 s[48:49], s[50:51], s[48:49]
	v_cmp_gt_i32_e64 s[50:51], v107, v82
	v_cndmask_b32_e64 v67, v132, v67, s[48:49]
	v_cmp_le_i32_e64 s[48:49], v107, v106
	s_and_b64 s[50:51], s[44:45], s[50:51]
	v_or_b32_e32 v107, 3, v83
	s_and_b64 s[48:49], s[50:51], s[48:49]
	v_cmp_gt_i32_e64 s[50:51], v107, v82
	v_cndmask_b32_e64 v68, v132, v68, s[48:49]
	v_cmp_le_i32_e64 s[48:49], v107, v106
	s_and_b64 s[50:51], s[44:45], s[50:51]
	v_or_b32_e32 v107, 8, v83
	s_and_b64 s[48:49], s[50:51], s[48:49]
	v_cmp_gt_i32_e64 s[50:51], v107, v82
	v_cndmask_b32_e64 v69, v132, v69, s[48:49]
	v_cmp_le_i32_e64 s[48:49], v107, v106
	s_and_b64 s[50:51], s[44:45], s[50:51]
	v_or_b32_e32 v107, 9, v83
	s_and_b64 s[48:49], s[50:51], s[48:49]
	v_cmp_gt_i32_e64 s[50:51], v107, v82
	v_cndmask_b32_e64 v70, v132, v70, s[48:49]
	v_cmp_le_i32_e64 s[48:49], v107, v106
	s_and_b64 s[50:51], s[44:45], s[50:51]
	v_or_b32_e32 v107, 10, v83
	s_and_b64 s[48:49], s[50:51], s[48:49]
	v_cmp_gt_i32_e64 s[50:51], v107, v82
	v_cndmask_b32_e64 v71, v132, v71, s[48:49]
	v_cmp_le_i32_e64 s[48:49], v107, v106
	s_and_b64 s[50:51], s[44:45], s[50:51]
	v_or_b32_e32 v107, 11, v83
	s_and_b64 s[48:49], s[50:51], s[48:49]
	v_cmp_gt_i32_e64 s[50:51], v107, v82
	v_cndmask_b32_e64 v72, v132, v72, s[48:49]
	v_cmp_le_i32_e64 s[48:49], v107, v106
	s_and_b64 s[50:51], s[44:45], s[50:51]
	v_or_b32_e32 v107, 16, v83
	s_and_b64 s[48:49], s[50:51], s[48:49]
	v_cmp_gt_i32_e64 s[50:51], v107, v82
	v_cndmask_b32_e64 v73, v132, v73, s[48:49]
	v_cmp_le_i32_e64 s[48:49], v107, v106
	s_and_b64 s[50:51], s[44:45], s[50:51]
	v_or_b32_e32 v107, 17, v83
	s_and_b64 s[48:49], s[50:51], s[48:49]
	v_cmp_gt_i32_e64 s[50:51], v107, v82
	v_cndmask_b32_e64 v74, v132, v74, s[48:49]
	v_cmp_le_i32_e64 s[48:49], v107, v106
	s_and_b64 s[50:51], s[44:45], s[50:51]
	v_or_b32_e32 v107, 18, v83
	s_and_b64 s[48:49], s[50:51], s[48:49]
	v_cmp_gt_i32_e64 s[50:51], v107, v82
	v_cndmask_b32_e64 v75, v132, v75, s[48:49]
	v_cmp_le_i32_e64 s[48:49], v107, v106
	s_and_b64 s[50:51], s[44:45], s[50:51]
	v_or_b32_e32 v107, 19, v83
	s_and_b64 s[48:49], s[50:51], s[48:49]
	v_cmp_gt_i32_e64 s[50:51], v107, v82
	v_mfma_f32_32x32x16_bf16 v[18:33], v[18:21], v[2:5], 0
	v_cndmask_b32_e64 v76, v132, v76, s[48:49]
	v_cmp_le_i32_e64 s[48:49], v107, v106
	s_and_b64 s[50:51], s[44:45], s[50:51]
	v_or_b32_e32 v107, 24, v83
	s_and_b64 s[48:49], s[50:51], s[48:49]
	v_cmp_gt_i32_e64 s[50:51], v107, v82
	v_cndmask_b32_e64 v77, v132, v77, s[48:49]
	v_cmp_le_i32_e64 s[48:49], v107, v106
	s_and_b64 s[50:51], s[44:45], s[50:51]
	v_or_b32_e32 v107, 25, v83
	s_and_b64 s[48:49], s[50:51], s[48:49]
	v_cmp_gt_i32_e64 s[50:51], v107, v82
	v_max3_f32 v94, v66, s33, v67
	v_cndmask_b32_e64 v78, v132, v78, s[48:49]
	v_cmp_le_i32_e64 s[48:49], v107, v106
	s_and_b64 s[50:51], s[44:45], s[50:51]
	v_or_b32_e32 v107, 26, v83
	v_max3_f32 v94, v94, v68, v69
	s_and_b64 s[48:49], s[50:51], s[48:49]
	v_cmp_gt_i32_e64 s[50:51], v107, v82
	v_max3_f32 v94, v94, v70, v71
	v_cndmask_b32_e64 v79, v132, v79, s[48:49]
	v_cmp_le_i32_e64 s[48:49], v107, v106
	s_and_b64 s[50:51], s[44:45], s[50:51]
	v_or_b32_e32 v83, 27, v83
	v_max3_f32 v94, v94, v72, v73
	s_and_b64 s[48:49], s[50:51], s[48:49]
	v_cmp_gt_i32_e64 s[50:51], v83, v82
	v_mfma_f32_32x32x16_bf16 v[18:33], v[6:9], v[90:93], v[18:33]
	v_max3_f32 v94, v94, v74, v75
	v_cndmask_b32_e64 v80, v132, v80, s[48:49]
	v_cmp_le_i32_e64 s[48:49], v83, v106
	s_and_b64 s[44:45], s[44:45], s[50:51]
	v_max3_f32 v94, v94, v76, v77
	s_and_b64 s[44:45], s[44:45], s[48:49]
	v_max3_f32 v94, v94, v78, v79
	v_cndmask_b32_e64 v81, v132, v81, s[44:45]
	v_max3_f32 v83, v94, v80, v81
	v_or_b32_e32 v94, s86, v98
	v_cmp_gt_i32_e64 s[48:49], v94, v82
	v_cmp_le_i32_e64 s[44:45], v94, v106
	s_and_b64 s[48:49], s[42:43], s[48:49]
	s_and_b64 s[44:45], s[48:49], s[44:45]
	v_cndmask_b32_e64 v50, v132, v50, s[44:45]
	v_cmp_lt_i32_e64 s[44:45], v94, v106
	v_mfma_f32_32x32x16_bf16 v[18:33], v[10:13], v[138:141], v[18:33]
	s_and_b64 s[48:49], s[42:43], s[44:45]
	v_cmp_ge_i32_e64 s[44:45], v94, v82
	v_or_b32_e32 v107, 2, v94
	s_and_b64 s[44:45], s[48:49], s[44:45]
	v_cmp_gt_i32_e64 s[48:49], v107, v82
	v_cndmask_b32_e64 v51, v132, v51, s[44:45]
	v_cmp_le_i32_e64 s[44:45], v107, v106
	v_mfma_f32_32x32x16_bf16 v[2:17], v[160:163], v[2:5], 0
	s_and_b64 s[48:49], s[42:43], s[48:49]
	v_or_b32_e32 v107, 3, v94
	s_and_b64 s[44:45], s[48:49], s[44:45]
	v_cmp_gt_i32_e64 s[48:49], v107, v82
	v_cndmask_b32_e64 v52, v132, v52, s[44:45]
	v_cmp_le_i32_e64 s[44:45], v107, v106
	s_and_b64 s[48:49], s[42:43], s[48:49]
	v_or_b32_e32 v107, 8, v94
	s_and_b64 s[44:45], s[48:49], s[44:45]
	v_cmp_gt_i32_e64 s[48:49], v107, v82
	v_cndmask_b32_e64 v53, v132, v53, s[44:45]
	v_cmp_le_i32_e64 s[44:45], v107, v106
	s_and_b64 s[48:49], s[42:43], s[48:49]
	v_or_b32_e32 v107, 9, v94
	s_and_b64 s[44:45], s[48:49], s[44:45]
	v_cmp_gt_i32_e64 s[48:49], v107, v82
	v_mfma_f32_32x32x16_bf16 v[2:17], v[168:171], v[90:93], v[2:17]
	global_load_dwordx4 v[90:93], v[180:181], off offset:96
	v_cndmask_b32_e64 v54, v132, v54, s[44:45]
	v_cmp_le_i32_e64 s[44:45], v107, v106
	s_and_b64 s[48:49], s[42:43], s[48:49]
	v_or_b32_e32 v107, 10, v94
	s_and_b64 s[44:45], s[48:49], s[44:45]
	v_cmp_gt_i32_e64 s[48:49], v107, v82
	v_cndmask_b32_e64 v55, v132, v55, s[44:45]
	v_cmp_le_i32_e64 s[44:45], v107, v106
	s_and_b64 s[48:49], s[42:43], s[48:49]
	v_or_b32_e32 v107, 11, v94
	s_and_b64 s[44:45], s[48:49], s[44:45]
	v_cmp_gt_i32_e64 s[48:49], v107, v82
	v_cndmask_b32_e64 v56, v132, v56, s[44:45]
	v_cmp_le_i32_e64 s[44:45], v107, v106
	s_and_b64 s[48:49], s[42:43], s[48:49]
	v_or_b32_e32 v107, 16, v94
	s_and_b64 s[44:45], s[48:49], s[44:45]
	v_cmp_gt_i32_e64 s[48:49], v107, v82
	v_cndmask_b32_e64 v57, v132, v57, s[44:45]
	v_cmp_le_i32_e64 s[44:45], v107, v106
	s_and_b64 s[48:49], s[42:43], s[48:49]
	v_or_b32_e32 v107, 17, v94
	s_and_b64 s[44:45], s[48:49], s[44:45]
	v_cmp_gt_i32_e64 s[48:49], v107, v82
	v_cndmask_b32_e64 v58, v132, v58, s[44:45]
	v_cmp_le_i32_e64 s[44:45], v107, v106
	s_and_b64 s[48:49], s[42:43], s[48:49]
	v_or_b32_e32 v107, 18, v94
	s_and_b64 s[44:45], s[48:49], s[44:45]
	v_cmp_gt_i32_e64 s[48:49], v107, v82
	v_cndmask_b32_e64 v59, v132, v59, s[44:45]
	v_cmp_le_i32_e64 s[44:45], v107, v106
	s_and_b64 s[48:49], s[42:43], s[48:49]
	v_or_b32_e32 v107, 19, v94
	s_and_b64 s[44:45], s[48:49], s[44:45]
	v_cmp_gt_i32_e64 s[48:49], v107, v82
	v_cndmask_b32_e64 v60, v132, v60, s[44:45]
	v_cmp_le_i32_e64 s[44:45], v107, v106
	s_and_b64 s[48:49], s[42:43], s[48:49]
	v_or_b32_e32 v107, 24, v94
	s_and_b64 s[44:45], s[48:49], s[44:45]
	v_cmp_gt_i32_e64 s[48:49], v107, v82
	v_cndmask_b32_e64 v61, v132, v61, s[44:45]
	v_cmp_le_i32_e64 s[44:45], v107, v106
	s_and_b64 s[48:49], s[42:43], s[48:49]
	v_or_b32_e32 v107, 25, v94
	s_and_b64 s[44:45], s[48:49], s[44:45]
	v_cmp_gt_i32_e64 s[48:49], v107, v82
	v_mfma_f32_32x32x16_bf16 v[34:49], v[142:145], v[86:89], v[34:49]
	v_cndmask_b32_e64 v62, v132, v62, s[44:45]
	v_cmp_le_i32_e64 s[44:45], v107, v106
	s_and_b64 s[48:49], s[42:43], s[48:49]
	v_or_b32_e32 v107, 26, v94
	v_max3_f32 v83, v83, v50, v51
	s_and_b64 s[44:45], s[48:49], s[44:45]
	v_cmp_gt_i32_e64 s[48:49], v107, v82
	v_max3_f32 v83, v83, v52, v53
	v_cndmask_b32_e64 v63, v132, v63, s[44:45]
	v_cmp_le_i32_e64 s[44:45], v107, v106
	s_and_b64 s[48:49], s[42:43], s[48:49]
	v_or_b32_e32 v94, 27, v94
	v_max3_f32 v83, v83, v54, v55
	s_and_b64 s[44:45], s[48:49], s[44:45]
	v_cmp_gt_i32_e64 s[48:49], v94, v82
	v_max3_f32 v83, v83, v56, v57
	v_cndmask_b32_e64 v64, v132, v64, s[44:45]
	v_cmp_le_i32_e64 s[44:45], v94, v106
	s_and_b64 s[42:43], s[42:43], s[48:49]
	v_or_b32_e32 v144, s79, v98
	v_max3_f32 v83, v83, v58, v59
	s_and_b64 s[42:43], s[42:43], s[44:45]
	v_cmp_gt_i32_e64 s[44:45], v144, v82
	v_max3_f32 v83, v83, v60, v61
	v_cndmask_b32_e64 v65, v132, v65, s[42:43]
	v_cmp_le_i32_e64 s[42:43], v144, v106
	s_and_b64 s[44:45], s[40:41], s[44:45]
	v_max3_f32 v83, v83, v62, v63
	s_and_b64 s[42:43], s[44:45], s[42:43]
	v_max3_f32 v107, v83, v64, v65
	v_cndmask_b32_e64 v83, v132, v34, s[42:43]
	v_cmp_lt_i32_e64 s[42:43], v144, v106
	s_and_b64 s[44:45], s[40:41], s[42:43]
	v_cmp_ge_i32_e64 s[42:43], v144, v82
	s_and_b64 s[42:43], s[44:45], s[42:43]
	s_waitcnt vmcnt(2)
	v_mfma_f32_32x32x16_bf16 v[2:17], v[172:175], v[138:141], v[2:17]
	v_cndmask_b32_e64 v94, v132, v35, s[42:43]
	v_or_b32_e32 v35, 2, v144
	v_cmp_gt_i32_e64 s[44:45], v35, v82
	v_cmp_le_i32_e64 s[42:43], v35, v106
	s_and_b64 s[44:45], s[40:41], s[44:45]
	v_or_b32_e32 v35, 3, v144
	s_and_b64 s[42:43], s[44:45], s[42:43]
	v_cmp_gt_i32_e64 s[44:45], v35, v82
	v_max3_f32 v34, v107, v83, v94
	v_cndmask_b32_e64 v107, v132, v36, s[42:43]
	v_cmp_le_i32_e64 s[42:43], v35, v106
	s_and_b64 s[44:45], s[40:41], s[44:45]
	v_or_b32_e32 v35, 8, v144
	s_and_b64 s[42:43], s[44:45], s[42:43]
	v_cmp_gt_i32_e64 s[44:45], v35, v82
	v_cndmask_b32_e64 v137, v132, v37, s[42:43]
	v_cmp_le_i32_e64 s[42:43], v35, v106
	s_and_b64 s[44:45], s[40:41], s[44:45]
	v_or_b32_e32 v35, 9, v144
	s_and_b64 s[42:43], s[44:45], s[42:43]
	v_cmp_gt_i32_e64 s[44:45], v35, v82
	v_cndmask_b32_e64 v138, v132, v38, s[42:43]
	v_cmp_le_i32_e64 s[42:43], v35, v106
	s_and_b64 s[44:45], s[40:41], s[44:45]
	v_or_b32_e32 v35, 10, v144
	s_and_b64 s[42:43], s[44:45], s[42:43]
	v_cmp_gt_i32_e64 s[44:45], v35, v82
	v_cndmask_b32_e64 v139, v132, v39, s[42:43]
	v_cmp_le_i32_e64 s[42:43], v35, v106
	s_and_b64 s[44:45], s[40:41], s[44:45]
	v_or_b32_e32 v35, 11, v144
	s_and_b64 s[42:43], s[44:45], s[42:43]
	v_cmp_gt_i32_e64 s[44:45], v35, v82
	v_cndmask_b32_e64 v140, v132, v40, s[42:43]
	v_cmp_le_i32_e64 s[42:43], v35, v106
	s_and_b64 s[44:45], s[40:41], s[44:45]
	v_or_b32_e32 v35, 16, v144
	s_and_b64 s[42:43], s[44:45], s[42:43]
	v_cmp_gt_i32_e64 s[44:45], v35, v82
	v_cndmask_b32_e64 v141, v132, v41, s[42:43]
	v_cmp_le_i32_e64 s[42:43], v35, v106
	s_and_b64 s[44:45], s[40:41], s[44:45]
	v_or_b32_e32 v35, 17, v144
	s_and_b64 s[42:43], s[44:45], s[42:43]
	v_cmp_gt_i32_e64 s[44:45], v35, v82
	v_cndmask_b32_e64 v142, v132, v42, s[42:43]
	v_cmp_le_i32_e64 s[42:43], v35, v106
	s_and_b64 s[44:45], s[40:41], s[44:45]
	v_or_b32_e32 v35, 18, v144
	s_and_b64 s[42:43], s[44:45], s[42:43]
	v_cmp_gt_i32_e64 s[44:45], v35, v82
	v_cndmask_b32_e64 v143, v132, v43, s[42:43]
	v_cmp_le_i32_e64 s[42:43], v35, v106
	s_and_b64 s[44:45], s[40:41], s[44:45]
	v_or_b32_e32 v35, 19, v144
	s_and_b64 s[42:43], s[44:45], s[42:43]
	v_cmp_gt_i32_e64 s[44:45], v35, v82
	v_cndmask_b32_e64 v145, v132, v44, s[42:43]
	v_cmp_le_i32_e64 s[42:43], v35, v106
	s_and_b64 s[44:45], s[40:41], s[44:45]
	v_or_b32_e32 v35, 24, v144
	s_and_b64 s[42:43], s[44:45], s[42:43]
	v_cmp_gt_i32_e64 s[44:45], v35, v82
	v_cndmask_b32_e64 v146, v132, v45, s[42:43]
	v_cmp_le_i32_e64 s[42:43], v35, v106
	s_and_b64 s[44:45], s[40:41], s[44:45]
	v_or_b32_e32 v35, 25, v144
	s_and_b64 s[42:43], s[44:45], s[42:43]
	v_cmp_gt_i32_e64 s[44:45], v35, v82
	s_waitcnt vmcnt(1)
	v_mfma_f32_32x32x16_bf16 v[18:33], v[176:179], v[86:89], v[18:33]
	v_cndmask_b32_e64 v148, v132, v46, s[42:43]
	v_cmp_le_i32_e64 s[42:43], v35, v106
	s_and_b64 s[44:45], s[40:41], s[44:45]
	v_or_b32_e32 v35, 26, v144
	s_and_b64 s[42:43], s[44:45], s[42:43]
	v_cmp_gt_i32_e64 s[44:45], v35, v82
	v_cndmask_b32_e64 v149, v132, v47, s[42:43]
	v_cmp_le_i32_e64 s[42:43], v35, v106
	s_and_b64 s[44:45], s[40:41], s[44:45]
	v_or_b32_e32 v35, 27, v144
	s_and_b64 s[42:43], s[44:45], s[42:43]
	v_cmp_gt_i32_e64 s[44:45], v35, v82
	v_cndmask_b32_e64 v48, v132, v48, s[42:43]
	v_cmp_le_i32_e64 s[42:43], v35, v106
	s_and_b64 s[40:41], s[40:41], s[44:45]
	v_or_b32_e32 v35, s73, v98
	s_and_b64 s[40:41], s[40:41], s[42:43]
	v_cmp_gt_i32_e64 s[42:43], v35, v82
	v_cndmask_b32_e64 v49, v132, v49, s[40:41]
	v_cmp_le_i32_e64 s[40:41], v35, v106
	s_and_b64 s[42:43], s[38:39], s[42:43]
	s_and_b64 s[40:41], s[42:43], s[40:41]
	v_cndmask_b32_e64 v18, v132, v18, s[40:41]
	v_cmp_lt_i32_e64 s[40:41], v35, v106
	s_and_b64 s[42:43], s[38:39], s[40:41]
	v_cmp_ge_i32_e64 s[40:41], v35, v82
	v_or_b32_e32 v36, 2, v35
	s_and_b64 s[40:41], s[42:43], s[40:41]
	v_cmp_gt_i32_e64 s[42:43], v36, v82
	v_cndmask_b32_e64 v19, v132, v19, s[40:41]
	v_cmp_le_i32_e64 s[40:41], v36, v106
	s_and_b64 s[42:43], s[38:39], s[42:43]
	v_or_b32_e32 v36, 3, v35
	s_and_b64 s[40:41], s[42:43], s[40:41]
	v_cmp_gt_i32_e64 s[42:43], v36, v82
	v_cndmask_b32_e64 v20, v132, v20, s[40:41]
	v_cmp_le_i32_e64 s[40:41], v36, v106
	s_and_b64 s[42:43], s[38:39], s[42:43]
	v_or_b32_e32 v36, 8, v35
	s_and_b64 s[40:41], s[42:43], s[40:41]
	v_cmp_gt_i32_e64 s[42:43], v36, v82
	v_cndmask_b32_e64 v21, v132, v21, s[40:41]
	v_cmp_le_i32_e64 s[40:41], v36, v106
	s_and_b64 s[42:43], s[38:39], s[42:43]
	v_or_b32_e32 v36, 9, v35
	s_and_b64 s[40:41], s[42:43], s[40:41]
	v_cmp_gt_i32_e64 s[42:43], v36, v82
	v_cndmask_b32_e64 v22, v132, v22, s[40:41]
	v_cmp_le_i32_e64 s[40:41], v36, v106
	s_and_b64 s[42:43], s[38:39], s[42:43]
	v_or_b32_e32 v36, 10, v35
	s_and_b64 s[40:41], s[42:43], s[40:41]
	v_cmp_gt_i32_e64 s[42:43], v36, v82
	v_cndmask_b32_e64 v23, v132, v23, s[40:41]
	v_cmp_le_i32_e64 s[40:41], v36, v106
	s_and_b64 s[42:43], s[38:39], s[42:43]
	v_or_b32_e32 v36, 11, v35
	s_and_b64 s[40:41], s[42:43], s[40:41]
	v_cmp_gt_i32_e64 s[42:43], v36, v82
	v_cndmask_b32_e64 v24, v132, v24, s[40:41]
	v_cmp_le_i32_e64 s[40:41], v36, v106
	s_and_b64 s[42:43], s[38:39], s[42:43]
	v_or_b32_e32 v36, 16, v35
	s_and_b64 s[40:41], s[42:43], s[40:41]
	v_cmp_gt_i32_e64 s[42:43], v36, v82
	v_cndmask_b32_e64 v25, v132, v25, s[40:41]
	v_cmp_le_i32_e64 s[40:41], v36, v106
	s_and_b64 s[42:43], s[38:39], s[42:43]
	v_or_b32_e32 v36, 17, v35
	s_and_b64 s[40:41], s[42:43], s[40:41]
	v_cmp_gt_i32_e64 s[42:43], v36, v82
	v_cndmask_b32_e64 v26, v132, v26, s[40:41]
	v_cmp_le_i32_e64 s[40:41], v36, v106
	s_and_b64 s[42:43], s[38:39], s[42:43]
	v_or_b32_e32 v36, 18, v35
	s_and_b64 s[40:41], s[42:43], s[40:41]
	v_cmp_gt_i32_e64 s[42:43], v36, v82
	v_cndmask_b32_e64 v27, v132, v27, s[40:41]
	v_cmp_le_i32_e64 s[40:41], v36, v106
	s_and_b64 s[42:43], s[38:39], s[42:43]
	v_or_b32_e32 v36, 19, v35
	s_and_b64 s[40:41], s[42:43], s[40:41]
	v_cmp_gt_i32_e64 s[42:43], v36, v82
	v_max3_f32 v34, v34, v107, v137
	v_cndmask_b32_e64 v28, v132, v28, s[40:41]
	v_cmp_le_i32_e64 s[40:41], v36, v106
	s_and_b64 s[42:43], s[38:39], s[42:43]
	v_or_b32_e32 v36, 24, v35
	v_max3_f32 v34, v34, v138, v139
	s_and_b64 s[40:41], s[42:43], s[40:41]
	v_cmp_gt_i32_e64 s[42:43], v36, v82
	v_max3_f32 v34, v34, v140, v141
	v_cndmask_b32_e64 v29, v132, v29, s[40:41]
	v_cmp_le_i32_e64 s[40:41], v36, v106
	s_and_b64 s[42:43], s[38:39], s[42:43]
	v_or_b32_e32 v36, 25, v35
	v_max3_f32 v34, v34, v142, v143
	s_and_b64 s[40:41], s[42:43], s[40:41]
	v_cmp_gt_i32_e64 s[42:43], v36, v82
	v_max3_f32 v34, v34, v145, v146
	v_cndmask_b32_e64 v30, v132, v30, s[40:41]
	v_cmp_le_i32_e64 s[40:41], v36, v106
	s_and_b64 s[42:43], s[38:39], s[42:43]
	v_or_b32_e32 v36, 26, v35
	s_waitcnt vmcnt(0)
	v_mfma_f32_32x32x16_bf16 v[2:17], v[90:93], v[86:89], v[2:17]
	v_max3_f32 v34, v34, v148, v149
	s_and_b64 s[40:41], s[42:43], s[40:41]
	v_cmp_gt_i32_e64 s[42:43], v36, v82
	v_max3_f32 v34, v34, v48, v49
	v_cndmask_b32_e64 v31, v132, v31, s[40:41]
	v_cmp_le_i32_e64 s[40:41], v36, v106
	s_and_b64 s[42:43], s[38:39], s[42:43]
	v_or_b32_e32 v35, 27, v35
	v_max3_f32 v34, v34, v18, v19
	s_and_b64 s[40:41], s[42:43], s[40:41]
	v_cmp_gt_i32_e64 s[42:43], v35, v82
	v_max3_f32 v34, v34, v20, v21
	v_cndmask_b32_e64 v32, v132, v32, s[40:41]
	v_cmp_le_i32_e64 s[40:41], v35, v106
	s_and_b64 s[38:39], s[38:39], s[42:43]
	v_max3_f32 v34, v34, v22, v23
	s_and_b64 s[38:39], s[38:39], s[40:41]
	v_or_b32_e32 v35, s72, v98
	v_max3_f32 v34, v34, v24, v25
	v_cndmask_b32_e64 v33, v132, v33, s[38:39]
	s_and_b64 s[40:41], vcc, s[46:47]
	v_cmp_gt_i32_e64 s[38:39], v35, v82
	v_max3_f32 v34, v34, v26, v27
	s_and_b64 s[38:39], s[40:41], s[38:39]
	v_max3_f32 v34, v34, v28, v29
	v_cndmask_b32_e64 v2, v132, v2, s[38:39]
	s_and_b64 s[40:41], vcc, s[54:55]
	v_cmp_ge_i32_e64 s[38:39], v35, v82
	v_max3_f32 v34, v34, v30, v31
	s_and_b64 s[38:39], s[40:41], s[38:39]
	v_max3_f32 v34, v34, v32, v33
	v_cndmask_b32_e64 v3, v132, v3, s[38:39]
	v_max3_f32 v35, v34, v2, v3
	v_or_b32_e32 v34, s72, v117
	s_lshl_b32 s42, s78, 2
	v_cmp_gt_i32_e64 s[38:39], v34, v82
	v_mov_b32_e32 v34, s42
	s_waitcnt lgkmcnt(0)
	global_load_dword v34, v34, s[14:15]
	s_and_b64 s[40:41], vcc, s[58:59]
	s_and_b64 s[38:39], s[40:41], s[38:39]
	v_cndmask_b32_e64 v86, v132, v4, s[38:39]
	v_or_b32_e32 v4, s72, v118
	s_and_b64 s[40:41], vcc, s[74:75]
	v_cmp_gt_i32_e64 s[38:39], v4, v82
	s_and_b64 s[38:39], s[40:41], s[38:39]
	s_and_b64 s[40:41], vcc, s[88:89]
	v_cndmask_b32_e64 v87, v132, v5, s[38:39]
	v_or_b32_e32 v5, s72, v119
	v_cmp_gt_i32_e64 s[38:39], v5, v82
	s_and_b64 s[38:39], s[40:41], s[38:39]
	v_or_b32_e32 v5, s72, v120
	v_cndmask_b32_e64 v46, v132, v6, s[38:39]
	s_and_b64 s[40:41], vcc, s[90:91]
	v_cmp_gt_i32_e64 s[38:39], v5, v82
	s_and_b64 s[38:39], s[40:41], s[38:39]
	v_or_b32_e32 v5, s72, v121
	v_cndmask_b32_e64 v47, v132, v7, s[38:39]
	s_and_b64 s[40:41], vcc, s[94:95]
	v_cmp_gt_i32_e64 s[38:39], v5, v82
	s_and_b64 s[38:39], s[40:41], s[38:39]
	v_or_b32_e32 v5, s72, v122
	v_cndmask_b32_e64 v45, v132, v8, s[38:39]
	s_and_b64 s[40:41], vcc, s[96:97]
	v_cmp_gt_i32_e64 s[38:39], v5, v82
	s_and_b64 s[38:39], s[40:41], s[38:39]
	v_or_b32_e32 v5, s72, v123
	v_cndmask_b32_e64 v43, v132, v9, s[38:39]
	s_and_b64 s[40:41], vcc, s[20:21]
	v_cmp_gt_i32_e64 s[38:39], v5, v82
	s_and_b64 s[38:39], s[40:41], s[38:39]
	v_or_b32_e32 v5, s72, v124
	v_cndmask_b32_e64 v44, v132, v10, s[38:39]
	s_and_b64 s[40:41], vcc, s[22:23]
	v_cmp_gt_i32_e64 s[38:39], v5, v82
	s_and_b64 s[38:39], s[40:41], s[38:39]
	v_or_b32_e32 v5, s72, v125
	v_cndmask_b32_e64 v41, v132, v11, s[38:39]
	s_and_b64 s[40:41], vcc, s[24:25]
	v_cmp_gt_i32_e64 s[38:39], v5, v82
	s_and_b64 s[38:39], s[40:41], s[38:39]
	v_or_b32_e32 v5, s72, v126
	v_cndmask_b32_e64 v42, v132, v12, s[38:39]
	s_and_b64 s[40:41], vcc, s[26:27]
	v_cmp_gt_i32_e64 s[38:39], v5, v82
	s_and_b64 s[38:39], s[40:41], s[38:39]
	v_or_b32_e32 v5, s72, v127
	v_cndmask_b32_e64 v39, v132, v13, s[38:39]
	s_and_b64 s[40:41], vcc, s[28:29]
	v_cmp_gt_i32_e64 s[38:39], v5, v82
	s_and_b64 s[38:39], s[40:41], s[38:39]
	v_or_b32_e32 v5, s72, v128
	v_cndmask_b32_e64 v40, v132, v14, s[38:39]
	s_and_b64 s[40:41], vcc, s[30:31]
	v_cmp_gt_i32_e64 s[38:39], v5, v82
	v_max3_f32 v4, v35, v86, v87
	s_and_b64 s[38:39], s[40:41], s[38:39]
	v_or_b32_e32 v5, s72, v129
	v_max3_f32 v4, v4, v46, v47
	v_cndmask_b32_e64 v38, v132, v15, s[38:39]
	s_and_b64 s[40:41], vcc, s[34:35]
	v_cmp_gt_i32_e64 s[38:39], v5, v82
	v_max3_f32 v4, v4, v45, v43
	s_and_b64 s[38:39], s[40:41], s[38:39]
	v_or_b32_e32 v5, s72, v130
	v_max3_f32 v4, v4, v44, v41
	v_cndmask_b32_e64 v36, v132, v16, s[38:39]
	s_and_b64 s[38:39], vcc, s[36:37]
	v_cmp_gt_i32_e32 vcc, v5, v82
	v_max3_f32 v4, v4, v42, v39
	s_and_b64 vcc, s[38:39], vcc
	v_max3_f32 v4, v4, v40, v38
	v_cndmask_b32_e32 v37, v132, v17, vcc
	v_max3_f32 v4, v4, v36, v37
	ds_bpermute_b32 v5, v131, v4
	ds_write_b16 v108, v84 offset:1600
	ds_write_b16_d16_hi v108, v84 offset:1936
	ds_write_b16 v108, v85 offset:2272
	ds_write_b16_d16_hi v108, v85 offset:2608
	s_waitcnt lgkmcnt(0)
	s_barrier
	s_waitcnt vmcnt(0)
	v_max3_f32 v35, v4, v5, v34
	v_sub_f32_e32 v13, v74, v35
	v_mul_f32_e32 v13, 0x3fb8aa3b, v13
	v_sub_f32_e32 v4, v66, v35
	v_exp_f32_e32 v66, v13
	v_sub_f32_e32 v13, v75, v35
	v_mul_f32_e32 v13, 0x3fb8aa3b, v13
	v_sub_f32_e32 v5, v67, v35
	v_exp_f32_e32 v67, v13
	v_sub_f32_e32 v13, v76, v35
	v_mul_f32_e32 v13, 0x3fb8aa3b, v13
	v_sub_f32_e32 v6, v68, v35
	v_exp_f32_e32 v68, v13
	v_sub_f32_e32 v13, v77, v35
	v_mul_f32_e32 v13, 0x3fb8aa3b, v13
	v_sub_f32_e32 v7, v69, v35
	v_exp_f32_e32 v69, v13
	v_sub_f32_e32 v13, v78, v35
	v_mul_f32_e32 v13, 0x3fb8aa3b, v13
	v_sub_f32_e32 v9, v70, v35
	v_exp_f32_e32 v70, v13
	v_sub_f32_e32 v13, v79, v35
	v_mul_f32_e32 v13, 0x3fb8aa3b, v13
	v_sub_f32_e32 v10, v71, v35
	v_exp_f32_e32 v71, v13
	v_sub_f32_e32 v13, v80, v35
	v_mul_f32_e32 v13, 0x3fb8aa3b, v13
	v_sub_f32_e32 v11, v72, v35
	v_exp_f32_e32 v72, v13
	v_sub_f32_e32 v13, v81, v35
	v_mul_f32_e32 v13, 0x3fb8aa3b, v13
	v_sub_f32_e32 v12, v73, v35
	v_exp_f32_e32 v73, v13
	v_sub_f32_e32 v13, v50, v35
	v_mul_f32_e32 v13, 0x3fb8aa3b, v13
	v_exp_f32_e32 v74, v13
	v_sub_f32_e32 v13, v51, v35
	v_mul_f32_e32 v13, 0x3fb8aa3b, v13
	v_exp_f32_e32 v75, v13
	v_sub_f32_e32 v13, v52, v35
	v_mul_f32_e32 v13, 0x3fb8aa3b, v13
	v_exp_f32_e32 v76, v13
	v_sub_f32_e32 v13, v53, v35
	v_mul_f32_e32 v13, 0x3fb8aa3b, v13
	v_exp_f32_e32 v77, v13
	v_sub_f32_e32 v13, v54, v35
	v_mul_f32_e32 v13, 0x3fb8aa3b, v13
	v_exp_f32_e32 v78, v13
	v_sub_f32_e32 v13, v55, v35
	v_mul_f32_e32 v13, 0x3fb8aa3b, v13
	v_exp_f32_e32 v79, v13
	v_sub_f32_e32 v13, v56, v35
	v_mul_f32_e32 v13, 0x3fb8aa3b, v13
	v_exp_f32_e32 v80, v13
	v_sub_f32_e32 v13, v57, v35
	v_mul_f32_e32 v13, 0x3fb8aa3b, v13
	v_exp_f32_e32 v81, v13
	v_sub_f32_e32 v13, v58, v35
	v_mul_f32_e32 v13, 0x3fb8aa3b, v13
	v_exp_f32_e32 v82, v13
	v_sub_f32_e32 v13, v59, v35
	v_mul_f32_e32 v13, 0x3fb8aa3b, v13
	v_exp_f32_e32 v84, v13
	v_sub_f32_e32 v13, v60, v35
	v_mul_f32_e32 v13, 0x3fb8aa3b, v13
	v_exp_f32_e32 v60, v13
	v_sub_f32_e32 v13, v61, v35
	v_mul_f32_e32 v13, 0x3fb8aa3b, v13
	v_exp_f32_e32 v61, v13
	v_sub_f32_e32 v13, v62, v35
	v_mul_f32_e32 v13, 0x3fb8aa3b, v13
	v_exp_f32_e32 v62, v13
	v_sub_f32_e32 v13, v63, v35
	v_mul_f32_e32 v13, 0x3fb8aa3b, v13
	v_exp_f32_e32 v63, v13
	v_sub_f32_e32 v13, v64, v35
	v_mul_f32_e32 v13, 0x3fb8aa3b, v13
	v_exp_f32_e32 v64, v13
	v_sub_f32_e32 v13, v65, v35
	v_mul_f32_e32 v13, 0x3fb8aa3b, v13
	v_mul_f32_e32 v4, 0x3fb8aa3b, v4
	v_exp_f32_e32 v65, v13
	v_sub_f32_e32 v13, v83, v35
	v_exp_f32_e32 v4, v4
	v_mul_f32_e32 v5, 0x3fb8aa3b, v5
	v_mul_f32_e32 v13, 0x3fb8aa3b, v13
	v_exp_f32_e32 v5, v5
	v_mul_f32_e32 v6, 0x3fb8aa3b, v6
	v_exp_f32_e32 v83, v13
	v_sub_f32_e32 v13, v94, v35
	v_exp_f32_e32 v6, v6
	v_mul_f32_e32 v7, 0x3fb8aa3b, v7
	v_mul_f32_e32 v13, 0x3fb8aa3b, v13
	v_exp_f32_e32 v7, v7
	v_mul_f32_e32 v9, 0x3fb8aa3b, v9
	v_exp_f32_e32 v85, v13
	v_sub_f32_e32 v13, v107, v35
	v_add_f32_e32 v8, 0, v4
	v_exp_f32_e32 v9, v9
	v_mul_f32_e32 v10, 0x3fb8aa3b, v10
	v_mul_f32_e32 v13, 0x3fb8aa3b, v13
	v_add_f32_e32 v8, v5, v8
	v_exp_f32_e32 v10, v10
	v_mul_f32_e32 v11, 0x3fb8aa3b, v11
	v_exp_f32_e32 v88, v13
	v_sub_f32_e32 v13, v137, v35
	v_add_f32_e32 v8, v6, v8
	v_exp_f32_e32 v11, v11
	v_mul_f32_e32 v12, 0x3fb8aa3b, v12
	v_mul_f32_e32 v13, 0x3fb8aa3b, v13
	v_add_f32_e32 v8, v7, v8
	v_exp_f32_e32 v12, v12
	v_exp_f32_e32 v89, v13
	v_sub_f32_e32 v13, v138, v35
	v_add_f32_e32 v8, v9, v8
	v_mul_f32_e32 v13, 0x3fb8aa3b, v13
	v_add_f32_e32 v8, v10, v8
	v_exp_f32_e32 v90, v13
	v_sub_f32_e32 v13, v139, v35
	v_add_f32_e32 v8, v11, v8
	v_mul_f32_e32 v13, 0x3fb8aa3b, v13
	v_add_f32_e32 v8, v12, v8
	v_exp_f32_e32 v91, v13
	v_sub_f32_e32 v13, v140, v35
	v_add_f32_e32 v8, v66, v8
	v_mul_f32_e32 v13, 0x3fb8aa3b, v13
	v_add_f32_e32 v8, v67, v8
	v_exp_f32_e32 v92, v13
	v_sub_f32_e32 v13, v141, v35
	v_add_f32_e32 v8, v68, v8
	v_mul_f32_e32 v13, 0x3fb8aa3b, v13
	v_add_f32_e32 v8, v69, v8
	v_exp_f32_e32 v93, v13
	v_sub_f32_e32 v13, v142, v35
	v_add_f32_e32 v8, v70, v8
	v_mul_f32_e32 v13, 0x3fb8aa3b, v13
	v_add_f32_e32 v8, v71, v8
	v_exp_f32_e32 v94, v13
	v_sub_f32_e32 v13, v143, v35
	v_add_f32_e32 v8, v72, v8
	v_mul_f32_e32 v13, 0x3fb8aa3b, v13
	v_add_f32_e32 v8, v73, v8
	v_exp_f32_e32 v107, v13
	v_sub_f32_e32 v13, v145, v35
	v_add_f32_e32 v8, v74, v8
	v_mul_f32_e32 v13, 0x3fb8aa3b, v13
	v_add_f32_e32 v8, v75, v8
	v_exp_f32_e32 v137, v13
	v_sub_f32_e32 v13, v146, v35
	v_add_f32_e32 v8, v76, v8
	v_mul_f32_e32 v13, 0x3fb8aa3b, v13
	v_add_f32_e32 v8, v77, v8
	v_exp_f32_e32 v138, v13
	v_sub_f32_e32 v13, v148, v35
	v_add_f32_e32 v8, v78, v8
	v_mul_f32_e32 v13, 0x3fb8aa3b, v13
	v_add_f32_e32 v8, v79, v8
	v_exp_f32_e32 v139, v13
	v_sub_f32_e32 v13, v149, v35
	v_add_f32_e32 v8, v80, v8
	v_mul_f32_e32 v13, 0x3fb8aa3b, v13
	v_add_f32_e32 v8, v81, v8
	v_exp_f32_e32 v140, v13
	v_sub_f32_e32 v13, v48, v35
	v_add_f32_e32 v8, v82, v8
	v_mul_f32_e32 v13, 0x3fb8aa3b, v13
	v_add_f32_e32 v8, v84, v8
	v_exp_f32_e32 v141, v13
	v_sub_f32_e32 v13, v49, v35
	v_add_f32_e32 v8, v60, v8
	v_mul_f32_e32 v13, 0x3fb8aa3b, v13
	v_add_f32_e32 v8, v61, v8
	v_exp_f32_e32 v142, v13
	v_sub_f32_e32 v13, v18, v35
	v_add_f32_e32 v8, v62, v8
	v_mul_f32_e32 v13, 0x3fb8aa3b, v13
	v_add_f32_e32 v8, v63, v8
	v_exp_f32_e32 v143, v13
	v_sub_f32_e32 v13, v19, v35
	v_add_f32_e32 v8, v64, v8
	v_mul_f32_e32 v13, 0x3fb8aa3b, v13
	v_add_f32_e32 v8, v65, v8
	v_exp_f32_e32 v144, v13
	v_sub_f32_e32 v13, v20, v35
	v_add_f32_e32 v8, v83, v8
	v_mul_f32_e32 v13, 0x3fb8aa3b, v13
	v_add_f32_e32 v8, v85, v8
	v_exp_f32_e32 v145, v13
	v_sub_f32_e32 v13, v21, v35
	v_add_f32_e32 v8, v88, v8
	v_mul_f32_e32 v13, 0x3fb8aa3b, v13
	v_add_f32_e32 v8, v89, v8
	v_exp_f32_e32 v146, v13
	v_sub_f32_e32 v13, v22, v35
	v_add_f32_e32 v8, v90, v8
	v_mul_f32_e32 v13, 0x3fb8aa3b, v13
	v_add_f32_e32 v8, v91, v8
	v_exp_f32_e32 v148, v13
	v_sub_f32_e32 v13, v23, v35
	v_add_f32_e32 v8, v92, v8
	v_mul_f32_e32 v13, 0x3fb8aa3b, v13
	v_add_f32_e32 v8, v93, v8
	v_exp_f32_e32 v149, v13
	v_sub_f32_e32 v13, v24, v35
	v_add_f32_e32 v8, v94, v8
	v_mul_f32_e32 v13, 0x3fb8aa3b, v13
	v_add_f32_e32 v8, v107, v8
	v_exp_f32_e32 v150, v13
	v_sub_f32_e32 v13, v25, v35
	v_add_f32_e32 v8, v137, v8
	v_mul_f32_e32 v13, 0x3fb8aa3b, v13
	v_add_f32_e32 v8, v138, v8
	v_exp_f32_e32 v151, v13
	v_sub_f32_e32 v13, v26, v35
	v_add_f32_e32 v8, v139, v8
	v_mul_f32_e32 v13, 0x3fb8aa3b, v13
	v_add_f32_e32 v8, v140, v8
	v_exp_f32_e32 v152, v13
	v_sub_f32_e32 v13, v27, v35
	v_add_f32_e32 v8, v141, v8
	v_mul_f32_e32 v13, 0x3fb8aa3b, v13
	v_add_f32_e32 v8, v142, v8
	v_exp_f32_e32 v153, v13
	v_sub_f32_e32 v13, v28, v35
	v_add_f32_e32 v8, v143, v8
	v_mul_f32_e32 v13, 0x3fb8aa3b, v13
	v_add_f32_e32 v8, v144, v8
	v_exp_f32_e32 v154, v13
	v_sub_f32_e32 v13, v29, v35
	v_add_f32_e32 v8, v145, v8
	v_mul_f32_e32 v13, 0x3fb8aa3b, v13
	v_add_f32_e32 v8, v146, v8
	v_exp_f32_e32 v155, v13
	v_sub_f32_e32 v13, v30, v35
	v_add_f32_e32 v8, v148, v8
	v_mul_f32_e32 v13, 0x3fb8aa3b, v13
	v_add_f32_e32 v8, v149, v8
	v_exp_f32_e32 v156, v13
	v_sub_f32_e32 v13, v31, v35
	v_add_f32_e32 v8, v150, v8
	v_mul_f32_e32 v13, 0x3fb8aa3b, v13
	v_add_f32_e32 v8, v151, v8
	v_exp_f32_e32 v157, v13
	v_sub_f32_e32 v13, v32, v35
	v_add_f32_e32 v8, v152, v8
	v_mul_f32_e32 v13, 0x3fb8aa3b, v13
	v_sub_f32_e32 v2, v2, v35
	v_add_f32_e32 v8, v153, v8
	v_exp_f32_e32 v158, v13
	v_sub_f32_e32 v13, v33, v35
	v_mul_f32_e32 v2, 0x3fb8aa3b, v2
	v_add_f32_e32 v8, v154, v8
	v_mul_f32_e32 v13, 0x3fb8aa3b, v13
	v_exp_f32_e32 v160, v2
	v_sub_f32_e32 v2, v3, v35
	v_add_f32_e32 v8, v155, v8
	v_exp_f32_e32 v159, v13
	v_mul_f32_e32 v2, 0x3fb8aa3b, v2
	v_add_f32_e32 v8, v156, v8
	v_exp_f32_e32 v161, v2
	v_bfe_u32 v2, v9, 16, 1
	v_bfe_u32 v3, v7, 16, 1
	v_bfe_u32 v17, v5, 16, 1
	v_bfe_u32 v18, v4, 16, 1
	v_add_f32_e32 v8, v157, v8
	v_add3_u32 v18, v4, v18, s76
	v_add3_u32 v17, v5, v17, s76
	v_add3_u32 v19, v7, v3, s76
	v_add3_u32 v20, v9, v2, s76
	ds_read2_b64 v[2:5], v133 offset1:2
	v_add_f32_e32 v8, v158, v8
	v_add_f32_e32 v14, v159, v8
	v_bfe_u32 v8, v12, 16, 1
	v_bfe_u32 v16, v6, 16, 1
	v_add3_u32 v16, v6, v16, s76
	v_add3_u32 v12, v12, v8, s76
	ds_read2_b64 v[6:9], v134 offset0:64 offset1:66
	v_bfe_u32 v13, v11, 16, 1
	v_bfe_u32 v15, v10, 16, 1
	v_add3_u32 v10, v10, v15, s76
	v_add3_u32 v11, v11, v13, s76
	v_perm_b32 v13, v12, v11, s77
	v_perm_b32 v12, v10, v20, s77
	v_perm_b32 v11, v19, v16, s77
	v_perm_b32 v10, v17, v18, s77
	ds_read2_b64 v[48:51], v133 offset0:4 offset1:6
	v_bfe_u32 v52, v73, 16, 1
	s_waitcnt lgkmcnt(2)
	v_mfma_f32_32x32x16_bf16 v[18:33], v[2:5], v[10:13], 0
	v_add_f32_e32 v2, v160, v14
	v_add_f32_e32 v162, v161, v2
	v_sub_f32_e32 v2, v86, v35
	v_bfe_u32 v53, v72, 16, 1
	v_bfe_u32 v54, v71, 16, 1
	v_bfe_u32 v55, v70, 16, 1
	v_bfe_u32 v56, v69, 16, 1
	v_bfe_u32 v57, v68, 16, 1
	v_bfe_u32 v58, v67, 16, 1
	v_bfe_u32 v59, v66, 16, 1
	v_mul_f32_e32 v2, 0x3fb8aa3b, v2
	v_add3_u32 v66, v66, v59, s76
	v_add3_u32 v67, v67, v58, s76
	v_add3_u32 v57, v68, v57, s76
	v_add3_u32 v56, v69, v56, s76
	v_add3_u32 v58, v70, v55, s76
	v_add3_u32 v68, v71, v54, s76
	v_add3_u32 v59, v72, v53, s76
	v_add3_u32 v69, v73, v52, s76
	ds_read2_b64 v[52:55], v134 offset0:68 offset1:70
	v_exp_f32_e32 v86, v2
	s_waitcnt lgkmcnt(2)
	v_mfma_f32_32x32x16_bf16 v[2:17], v[6:9], v[10:13], 0
	v_sub_f32_e32 v46, v46, v35
	v_sub_f32_e32 v87, v87, v35
	v_perm_b32 v59, v69, v59, s77
	v_perm_b32 v58, v68, v58, s77
	v_perm_b32 v57, v56, v57, s77
	v_perm_b32 v56, v67, v66, s77
	v_mul_f32_e32 v46, 0x3fb8aa3b, v46
	v_exp_f32_e32 v67, v46
	s_waitcnt lgkmcnt(1)
	v_mfma_f32_32x32x16_bf16 v[18:33], v[48:51], v[56:59], v[18:33]
	v_mul_f32_e32 v48, 0x3fb8aa3b, v87
	v_sub_f32_e32 v46, v47, v35
	v_exp_f32_e32 v66, v48
	v_mul_f32_e32 v68, 0x3fb8aa3b, v46
	v_bfe_u32 v46, v78, 16, 1
	v_bfe_u32 v47, v77, 16, 1
	v_bfe_u32 v48, v76, 16, 1
	v_bfe_u32 v49, v75, 16, 1
	s_waitcnt lgkmcnt(0)
	v_mfma_f32_32x32x16_bf16 v[2:17], v[52:55], v[56:59], v[2:17]
	v_add3_u32 v58, v75, v49, s76
	v_add3_u32 v55, v76, v48, s76
	v_add3_u32 v59, v77, v47, s76
	v_add3_u32 v56, v78, v46, s76
	ds_read2_b64 v[46:49], v133 offset0:8 offset1:10
	v_bfe_u32 v50, v81, 16, 1
	v_bfe_u32 v51, v80, 16, 1
	v_bfe_u32 v52, v79, 16, 1
	v_bfe_u32 v53, v74, 16, 1
	v_add3_u32 v54, v74, v53, s76
	v_add3_u32 v69, v79, v52, s76
	v_add3_u32 v57, v80, v51, s76
	v_add3_u32 v70, v81, v50, s76
	ds_read2_b64 v[50:53], v134 offset0:72 offset1:74
	v_perm_b32 v57, v70, v57, s77
	v_perm_b32 v56, v69, v56, s77
	v_perm_b32 v55, v59, v55, s77
	v_perm_b32 v54, v58, v54, s77
	v_exp_f32_e32 v58, v68
	v_sub_f32_e32 v45, v45, v35
	s_waitcnt lgkmcnt(1)
	v_mfma_f32_32x32x16_bf16 v[18:33], v[46:49], v[54:57], v[18:33]
	v_add_f32_e32 v46, v86, v162
	v_add_f32_e32 v46, v66, v46
	v_add_f32_e32 v46, v67, v46
	v_add_f32_e32 v59, v58, v46
	v_bfe_u32 v46, v62, 16, 1
	v_bfe_u32 v47, v61, 16, 1
	v_bfe_u32 v48, v60, 16, 1
	v_bfe_u32 v49, v84, 16, 1
	s_waitcnt lgkmcnt(0)
	v_mfma_f32_32x32x16_bf16 v[2:17], v[50:53], v[54:57], v[2:17]
	v_bfe_u32 v50, v65, 16, 1
	v_bfe_u32 v51, v64, 16, 1
	v_bfe_u32 v52, v63, 16, 1
	v_bfe_u32 v53, v82, 16, 1
	v_add3_u32 v68, v84, v49, s76
	v_add3_u32 v55, v60, v48, s76
	v_add3_u32 v60, v61, v47, s76
	v_add3_u32 v56, v62, v46, s76
	ds_read2_b64 v[46:49], v133 offset0:12 offset1:14
	v_add3_u32 v54, v82, v53, s76
	v_add3_u32 v61, v63, v52, s76
	v_add3_u32 v57, v64, v51, s76
	v_add3_u32 v62, v65, v50, s76
	ds_read2_b64 v[50:53], v134 offset0:76 offset1:78
	v_sub_f32_e32 v43, v43, v35
	v_mul_f32_e32 v45, 0x3fb8aa3b, v45
	v_perm_b32 v57, v62, v57, s77
	v_perm_b32 v56, v61, v56, s77
	v_perm_b32 v55, v60, v55, s77
	v_perm_b32 v54, v68, v54, s77
	v_mul_f32_e32 v43, 0x3fb8aa3b, v43
	v_exp_f32_e32 v60, v45
	s_waitcnt lgkmcnt(1)
	v_mfma_f32_32x32x16_bf16 v[18:33], v[46:49], v[54:57], v[18:33]
	v_exp_f32_e32 v61, v43
	v_sub_f32_e32 v43, v44, v35
	v_bfe_u32 v44, v90, 16, 1
	v_bfe_u32 v45, v89, 16, 1
	v_bfe_u32 v46, v88, 16, 1
	v_bfe_u32 v47, v85, 16, 1
	v_bfe_u32 v48, v92, 16, 1
	s_waitcnt lgkmcnt(0)
	v_mfma_f32_32x32x16_bf16 v[2:17], v[50:53], v[54:57], v[2:17]
	v_bfe_u32 v49, v91, 16, 1
	v_bfe_u32 v50, v83, 16, 1
	v_add3_u32 v56, v85, v47, s76
	v_add3_u32 v53, v88, v46, s76
	v_add3_u32 v57, v89, v45, s76
	v_add3_u32 v54, v90, v44, s76
	ds_read2_b64 v[44:47], v133 offset0:16 offset1:18
	v_add3_u32 v52, v83, v50, s76
	v_add3_u32 v63, v91, v49, s76
	v_add3_u32 v55, v92, v48, s76
	ds_read2_b64 v[48:51], v134 offset0:80 offset1:82
	v_mul_f32_e32 v43, 0x3fb8aa3b, v43
	v_exp_f32_e32 v62, v43
	v_bfe_u32 v43, v93, 16, 1
	v_add3_u32 v43, v93, v43, s76
	v_perm_b32 v55, v43, v55, s77
	v_add_f32_e32 v43, v60, v59
	v_sub_f32_e32 v41, v41, v35
	v_perm_b32 v54, v63, v54, s77
	v_perm_b32 v53, v57, v53, s77
	v_perm_b32 v52, v56, v52, s77
	v_add_f32_e32 v43, v61, v43
	v_mul_f32_e32 v41, 0x3fb8aa3b, v41
	s_waitcnt lgkmcnt(1)
	v_mfma_f32_32x32x16_bf16 v[18:33], v[44:47], v[52:55], v[18:33]
	v_add_f32_e32 v56, v62, v43
	v_exp_f32_e32 v57, v41
	v_sub_f32_e32 v41, v42, v35
	v_bfe_u32 v42, v139, 16, 1
	v_bfe_u32 v43, v138, 16, 1
	v_bfe_u32 v44, v137, 16, 1
	v_bfe_u32 v45, v107, 16, 1
	s_waitcnt lgkmcnt(0)
	v_mfma_f32_32x32x16_bf16 v[2:17], v[48:51], v[52:55], v[2:17]
	v_bfe_u32 v46, v142, 16, 1
	v_bfe_u32 v47, v141, 16, 1
	v_bfe_u32 v48, v140, 16, 1
	v_bfe_u32 v49, v94, 16, 1
	v_add3_u32 v54, v107, v45, s76
	v_add3_u32 v51, v137, v44, s76
	v_add3_u32 v55, v138, v43, s76
	v_add3_u32 v52, v139, v42, s76
	ds_read2_b64 v[42:45], v133 offset0:20 offset1:22
	v_add3_u32 v50, v94, v49, s76
	v_add3_u32 v59, v140, v48, s76
	v_add3_u32 v53, v141, v47, s76
	v_add3_u32 v63, v142, v46, s76
	ds_read2_b64 v[46:49], v134 offset0:84 offset1:86
	v_sub_f32_e32 v39, v39, v35
	v_perm_b32 v53, v63, v53, s77
	v_perm_b32 v52, v59, v52, s77
	v_perm_b32 v51, v55, v51, s77
	v_perm_b32 v50, v54, v50, s77
	v_mul_f32_e32 v41, 0x3fb8aa3b, v41
	v_mul_f32_e32 v39, 0x3fb8aa3b, v39
	s_waitcnt lgkmcnt(1)
	v_mfma_f32_32x32x16_bf16 v[18:33], v[42:45], v[50:53], v[18:33]
	v_exp_f32_e32 v54, v41
	v_exp_f32_e32 v55, v39
	v_sub_f32_e32 v39, v40, v35
	v_bfe_u32 v40, v148, 16, 1
	v_bfe_u32 v41, v146, 16, 1
	v_bfe_u32 v42, v145, 16, 1
	v_bfe_u32 v43, v144, 16, 1
	s_waitcnt lgkmcnt(0)
	v_mfma_f32_32x32x16_bf16 v[2:17], v[46:49], v[50:53], v[2:17]
	v_bfe_u32 v44, v151, 16, 1
	v_bfe_u32 v45, v150, 16, 1
	v_bfe_u32 v46, v149, 16, 1
	v_bfe_u32 v47, v143, 16, 1
	v_add3_u32 v52, v144, v43, s76
	v_add3_u32 v49, v145, v42, s76
	v_add3_u32 v53, v146, v41, s76
	v_add3_u32 v50, v148, v40, s76
	ds_read2_b64 v[40:43], v133 offset0:24 offset1:26
	v_add3_u32 v48, v143, v47, s76
	v_add3_u32 v59, v149, v46, s76
	v_add3_u32 v51, v150, v45, s76
	v_add3_u32 v63, v151, v44, s76
	ds_read2_b64 v[44:47], v134 offset0:88 offset1:90
	v_mul_f32_e32 v39, 0x3fb8aa3b, v39
	v_perm_b32 v48, v52, v48, s77
	v_exp_f32_e32 v52, v39
	v_add_f32_e32 v39, v57, v56
	v_add_f32_e32 v39, v54, v39
	v_perm_b32 v51, v63, v51, s77
	v_perm_b32 v50, v59, v50, s77
	v_perm_b32 v49, v53, v49, s77
	v_add_f32_e32 v39, v55, v39
	v_sub_f32_e32 v38, v38, v35
	s_waitcnt lgkmcnt(1)
	v_mfma_f32_32x32x16_bf16 v[18:33], v[40:43], v[48:51], v[18:33]
	v_add_f32_e32 v53, v52, v39
	v_mul_f32_e32 v56, 0x3fb8aa3b, v38
	v_bfe_u32 v38, v156, 16, 1
	v_bfe_u32 v39, v155, 16, 1
	v_bfe_u32 v40, v154, 16, 1
	v_bfe_u32 v41, v153, 16, 1
	v_bfe_u32 v42, v159, 16, 1
	s_waitcnt lgkmcnt(0)
	v_mfma_f32_32x32x16_bf16 v[2:17], v[44:47], v[48:51], v[2:17]
	v_bfe_u32 v43, v158, 16, 1
	v_bfe_u32 v44, v157, 16, 1
	v_bfe_u32 v45, v152, 16, 1
	v_add3_u32 v50, v153, v41, s76
	v_add3_u32 v47, v154, v40, s76
	v_add3_u32 v51, v155, v39, s76
	v_add3_u32 v48, v156, v38, s76
	ds_read2_b64 v[38:41], v133 offset0:28 offset1:30
	v_add3_u32 v46, v152, v45, s76
	v_add3_u32 v59, v157, v44, s76
	v_add3_u32 v49, v158, v43, s76
	v_add3_u32 v63, v159, v42, s76
	ds_read2_b64 v[42:45], v134 offset0:92 offset1:94
	v_sub_f32_e32 v36, v36, v35
	v_mul_f32_e32 v36, 0x3fb8aa3b, v36
	v_perm_b32 v47, v51, v47, s77
	v_exp_f32_e32 v51, v36
	v_sub_f32_e32 v36, v37, v35
	v_perm_b32 v49, v63, v49, s77
	v_perm_b32 v48, v59, v48, s77
	v_perm_b32 v46, v50, v46, s77
	v_mul_f32_e32 v36, 0x3fb8aa3b, v36
	v_exp_f32_e32 v50, v56
	s_waitcnt lgkmcnt(1)
	v_mfma_f32_32x32x16_bf16 v[18:33], v[38:41], v[46:49], v[18:33]
	v_exp_f32_e32 v56, v36
	v_bfe_u32 v36, v67, 16, 1
	v_bfe_u32 v37, v66, 16, 1
	v_bfe_u32 v38, v86, 16, 1
	v_bfe_u32 v39, v161, 16, 1
	v_bfe_u32 v40, v61, 16, 1
	v_bfe_u32 v41, v60, 16, 1
	s_waitcnt lgkmcnt(0)
	v_mfma_f32_32x32x16_bf16 v[2:17], v[42:45], v[46:49], v[2:17]
	v_add3_u32 v48, v161, v39, s76
	v_add3_u32 v45, v86, v38, s76
	v_add3_u32 v49, v66, v37, s76
	v_add3_u32 v46, v67, v36, s76
	ds_read2_b64 v[36:39], v133 offset0:32 offset1:34
	v_bfe_u32 v42, v58, 16, 1
	v_bfe_u32 v43, v160, 16, 1
	v_add3_u32 v44, v160, v43, s76
	v_add3_u32 v58, v58, v42, s76
	v_add3_u32 v47, v60, v41, s76
	v_add3_u32 v59, v61, v40, s76
	ds_read2_b64 v[40:43], v134 offset0:96 offset1:98
	v_perm_b32 v47, v59, v47, s77
	v_perm_b32 v46, v58, v46, s77
	v_perm_b32 v45, v49, v45, s77
	v_perm_b32 v44, v48, v44, s77
	v_sub_f32_e32 v34, v34, v35
	v_mul_f32_e32 v34, 0x3fb8aa3b, v34
	s_waitcnt lgkmcnt(1)
	v_mfma_f32_32x32x16_bf16 v[18:33], v[36:39], v[44:47], v[18:33]
	v_add_f32_e32 v36, v50, v53
	v_add_f32_e32 v36, v51, v36
	v_add_f32_e32 v48, v56, v36
	v_exp_f32_e32 v53, v34
	v_bfe_u32 v34, v52, 16, 1
	v_bfe_u32 v35, v55, 16, 1
	v_bfe_u32 v36, v54, 16, 1
	v_bfe_u32 v37, v57, 16, 1
	s_waitcnt lgkmcnt(0)
	v_mfma_f32_32x32x16_bf16 v[2:17], v[40:43], v[44:47], v[2:17]
	v_add3_u32 v46, v57, v37, s76
	v_add3_u32 v43, v54, v36, s76
	v_add3_u32 v47, v55, v35, s76
	v_add3_u32 v44, v52, v34, s76
	ds_read2_b64 v[34:37], v133 offset0:36 offset1:38
	ds_bpermute_b32 v49, v131, v48
	v_bfe_u32 v38, v56, 16, 1
	v_bfe_u32 v39, v51, 16, 1
	v_bfe_u32 v40, v50, 16, 1
	v_bfe_u32 v41, v62, 16, 1
	v_add3_u32 v42, v62, v41, s76
	v_add3_u32 v50, v50, v40, s76
	v_add3_u32 v45, v51, v39, s76
	v_add3_u32 v51, v56, v38, s76
	v_perm_b32 v45, v51, v45, s77
	v_perm_b32 v44, v50, v44, s77
	v_perm_b32 v43, v47, v43, s77
	v_perm_b32 v42, v46, v42, s77
	ds_read2_b64 v[38:41], v134 offset0:100 offset1:102
	v_ashrrev_i32_e32 v107, 31, v106
	s_waitcnt lgkmcnt(2)
	v_mfma_f32_32x32x16_bf16 v[18:33], v[34:37], v[42:45], v[18:33]
	s_waitcnt lgkmcnt(1)
	v_add_f32_e32 v34, v48, v49
	v_add_f32_e32 v34, v53, v34
	v_div_scale_f32 v35, s[38:39], v34, v34, 1.0
	v_rcp_f32_e32 v36, v35
	s_nop 0
	v_fma_f32 v37, -v35, v36, 1.0
	v_fmac_f32_e32 v36, v37, v36
	v_div_scale_f32 v37, vcc, 1.0, v34, 1.0
	s_waitcnt lgkmcnt(0)
	v_mfma_f32_32x32x16_bf16 v[2:17], v[38:41], v[42:45], v[2:17]
	v_mul_f32_e32 v38, v37, v36
	v_fma_f32 v39, -v35, v38, v37
	v_fmac_f32_e32 v38, v39, v36
	v_fma_f32 v35, -v35, v38, v37
	v_div_fmas_f32 v35, v35, v36, v38
	v_div_fixup_f32 v34, v35, v34, 1.0
	v_mov_b32_e32 v38, v18
	v_mov_b32_e32 v39, v20
	v_pk_mul_f32 v[38:39], v[38:39], v[34:35] op_sel_hi:[1,0]
	v_mov_b32_e32 v20, v19
	v_lshl_add_u64 v[36:37], v[106:107], 0, s[62:63]
	v_pk_mul_f32 v[18:19], v[20:21], v[34:35] op_sel_hi:[1,0]
	v_and_b32_sdwa v21, v38, v135 dst_sel:DWORD dst_unused:UNUSED_PAD src0_sel:WORD_1 src1_sel:DWORD
	v_lshlrev_b64 v[36:37], 11, v[36:37]
	v_add3_u32 v21, v38, v21, s76
	v_and_b32_sdwa v35, v19, v135 dst_sel:DWORD dst_unused:UNUSED_PAD src0_sel:WORD_1 src1_sel:DWORD
	v_and_b32_sdwa v38, v18, v135 dst_sel:DWORD dst_unused:UNUSED_PAD src0_sel:WORD_1 src1_sel:DWORD
	v_lshl_add_u64 v[36:37], s[84:85], 0, v[36:37]
	v_and_b32_sdwa v20, v39, v135 dst_sel:DWORD dst_unused:UNUSED_PAD src0_sel:WORD_1 src1_sel:DWORD
	v_add3_u32 v19, v19, v35, s76
	v_add3_u32 v18, v18, v38, s76
	v_lshl_add_u64 v[36:37], v[36:37], 0, s[70:71]
	v_add3_u32 v20, v39, v20, s76
	v_and_b32_e32 v19, 0xffff0000, v19
	v_and_b32_e32 v18, 0xffff0000, v18
	v_lshl_add_u64 v[36:37], v[36:37], 0, v[104:105]
	v_or_b32_sdwa v19, v19, v20 dst_sel:DWORD dst_unused:UNUSED_PAD src0_sel:DWORD src1_sel:WORD_1
	v_or_b32_sdwa v18, v18, v21 dst_sel:DWORD dst_unused:UNUSED_PAD src0_sel:DWORD src1_sel:WORD_1
	global_store_dwordx2 v[36:37], v[18:19], off offset:1024
	v_mov_b32_e32 v18, v2
	v_mov_b32_e32 v19, v4
	v_pk_mul_f32 v[18:19], v[18:19], v[34:35] op_sel_hi:[1,0]
	v_mov_b32_e32 v4, v3
	v_pk_mul_f32 v[2:3], v[4:5], v[34:35] op_sel_hi:[1,0]
	v_and_b32_sdwa v4, v19, v135 dst_sel:DWORD dst_unused:UNUSED_PAD src0_sel:WORD_1 src1_sel:DWORD
	v_and_b32_sdwa v5, v18, v135 dst_sel:DWORD dst_unused:UNUSED_PAD src0_sel:WORD_1 src1_sel:DWORD
	v_add3_u32 v5, v18, v5, s76
	v_add3_u32 v4, v19, v4, s76
	v_and_b32_sdwa v18, v3, v135 dst_sel:DWORD dst_unused:UNUSED_PAD src0_sel:WORD_1 src1_sel:DWORD
	v_and_b32_sdwa v19, v2, v135 dst_sel:DWORD dst_unused:UNUSED_PAD src0_sel:WORD_1 src1_sel:DWORD
	v_add3_u32 v3, v3, v18, s76
	v_add3_u32 v2, v2, v19, s76
	v_and_b32_e32 v3, 0xffff0000, v3
	v_and_b32_e32 v2, 0xffff0000, v2
	v_or_b32_sdwa v3, v3, v4 dst_sel:DWORD dst_unused:UNUSED_PAD src0_sel:DWORD src1_sel:WORD_1
	v_or_b32_sdwa v2, v2, v5 dst_sel:DWORD dst_unused:UNUSED_PAD src0_sel:DWORD src1_sel:WORD_1
	global_store_dwordx2 v[36:37], v[2:3], off offset:1088
	v_mov_b32_e32 v2, v22
	v_mov_b32_e32 v3, v24
	v_pk_mul_f32 v[2:3], v[2:3], v[34:35] op_sel_hi:[1,0]
	v_mov_b32_e32 v24, v23
	v_pk_mul_f32 v[4:5], v[24:25], v[34:35] op_sel_hi:[1,0]
	v_and_b32_sdwa v18, v3, v135 dst_sel:DWORD dst_unused:UNUSED_PAD src0_sel:WORD_1 src1_sel:DWORD
	v_and_b32_sdwa v19, v2, v135 dst_sel:DWORD dst_unused:UNUSED_PAD src0_sel:WORD_1 src1_sel:DWORD
	v_add3_u32 v2, v2, v19, s76
	v_add3_u32 v3, v3, v18, s76
	v_and_b32_sdwa v18, v5, v135 dst_sel:DWORD dst_unused:UNUSED_PAD src0_sel:WORD_1 src1_sel:DWORD
	v_and_b32_sdwa v19, v4, v135 dst_sel:DWORD dst_unused:UNUSED_PAD src0_sel:WORD_1 src1_sel:DWORD
	v_add3_u32 v5, v5, v18, s76
	v_add3_u32 v4, v4, v19, s76
	v_and_b32_e32 v5, 0xffff0000, v5
	v_and_b32_e32 v4, 0xffff0000, v4
	v_or_b32_sdwa v3, v5, v3 dst_sel:DWORD dst_unused:UNUSED_PAD src0_sel:DWORD src1_sel:WORD_1
	v_or_b32_sdwa v2, v4, v2 dst_sel:DWORD dst_unused:UNUSED_PAD src0_sel:DWORD src1_sel:WORD_1
	global_store_dwordx2 v[36:37], v[2:3], off offset:1040
	v_mov_b32_e32 v2, v6
	v_mov_b32_e32 v3, v8
	v_pk_mul_f32 v[2:3], v[2:3], v[34:35] op_sel_hi:[1,0]
	v_mov_b32_e32 v8, v7
	v_pk_mul_f32 v[4:5], v[8:9], v[34:35] op_sel_hi:[1,0]
	v_and_b32_sdwa v6, v3, v135 dst_sel:DWORD dst_unused:UNUSED_PAD src0_sel:WORD_1 src1_sel:DWORD
	v_and_b32_sdwa v7, v2, v135 dst_sel:DWORD dst_unused:UNUSED_PAD src0_sel:WORD_1 src1_sel:DWORD
	v_add3_u32 v2, v2, v7, s76
	v_add3_u32 v3, v3, v6, s76
	v_and_b32_sdwa v6, v5, v135 dst_sel:DWORD dst_unused:UNUSED_PAD src0_sel:WORD_1 src1_sel:DWORD
	v_and_b32_sdwa v7, v4, v135 dst_sel:DWORD dst_unused:UNUSED_PAD src0_sel:WORD_1 src1_sel:DWORD
	v_add3_u32 v5, v5, v6, s76
	v_add3_u32 v4, v4, v7, s76
	v_and_b32_e32 v5, 0xffff0000, v5
	v_and_b32_e32 v4, 0xffff0000, v4
	v_or_b32_sdwa v3, v5, v3 dst_sel:DWORD dst_unused:UNUSED_PAD src0_sel:DWORD src1_sel:WORD_1
	v_or_b32_sdwa v2, v4, v2 dst_sel:DWORD dst_unused:UNUSED_PAD src0_sel:DWORD src1_sel:WORD_1
	global_store_dwordx2 v[36:37], v[2:3], off offset:1104
	v_mov_b32_e32 v2, v26
	v_mov_b32_e32 v3, v28
	v_pk_mul_f32 v[2:3], v[2:3], v[34:35] op_sel_hi:[1,0]
	v_mov_b32_e32 v28, v27
	v_pk_mul_f32 v[4:5], v[28:29], v[34:35] op_sel_hi:[1,0]
	v_and_b32_sdwa v6, v3, v135 dst_sel:DWORD dst_unused:UNUSED_PAD src0_sel:WORD_1 src1_sel:DWORD
	v_and_b32_sdwa v7, v2, v135 dst_sel:DWORD dst_unused:UNUSED_PAD src0_sel:WORD_1 src1_sel:DWORD
	v_add3_u32 v2, v2, v7, s76
	v_add3_u32 v3, v3, v6, s76
	v_and_b32_sdwa v6, v5, v135 dst_sel:DWORD dst_unused:UNUSED_PAD src0_sel:WORD_1 src1_sel:DWORD
	v_and_b32_sdwa v7, v4, v135 dst_sel:DWORD dst_unused:UNUSED_PAD src0_sel:WORD_1 src1_sel:DWORD
	v_add3_u32 v5, v5, v6, s76
	v_add3_u32 v4, v4, v7, s76
	v_and_b32_e32 v5, 0xffff0000, v5
	v_and_b32_e32 v4, 0xffff0000, v4
	v_or_b32_sdwa v3, v5, v3 dst_sel:DWORD dst_unused:UNUSED_PAD src0_sel:DWORD src1_sel:WORD_1
	v_or_b32_sdwa v2, v4, v2 dst_sel:DWORD dst_unused:UNUSED_PAD src0_sel:DWORD src1_sel:WORD_1
	global_store_dwordx2 v[36:37], v[2:3], off offset:1056
	v_mov_b32_e32 v2, v10
	v_mov_b32_e32 v3, v12
	v_pk_mul_f32 v[2:3], v[2:3], v[34:35] op_sel_hi:[1,0]
	v_mov_b32_e32 v12, v11
	v_pk_mul_f32 v[4:5], v[12:13], v[34:35] op_sel_hi:[1,0]
	v_and_b32_sdwa v6, v3, v135 dst_sel:DWORD dst_unused:UNUSED_PAD src0_sel:WORD_1 src1_sel:DWORD
	v_and_b32_sdwa v7, v2, v135 dst_sel:DWORD dst_unused:UNUSED_PAD src0_sel:WORD_1 src1_sel:DWORD
	v_add3_u32 v2, v2, v7, s76
	v_add3_u32 v3, v3, v6, s76
	v_and_b32_sdwa v6, v5, v135 dst_sel:DWORD dst_unused:UNUSED_PAD src0_sel:WORD_1 src1_sel:DWORD
	v_and_b32_sdwa v7, v4, v135 dst_sel:DWORD dst_unused:UNUSED_PAD src0_sel:WORD_1 src1_sel:DWORD
	v_add3_u32 v5, v5, v6, s76
	v_add3_u32 v4, v4, v7, s76
	v_and_b32_e32 v5, 0xffff0000, v5
	v_and_b32_e32 v4, 0xffff0000, v4
	v_or_b32_sdwa v3, v5, v3 dst_sel:DWORD dst_unused:UNUSED_PAD src0_sel:DWORD src1_sel:WORD_1
	v_or_b32_sdwa v2, v4, v2 dst_sel:DWORD dst_unused:UNUSED_PAD src0_sel:DWORD src1_sel:WORD_1
	global_store_dwordx2 v[36:37], v[2:3], off offset:1120
	v_mov_b32_e32 v2, v30
	v_mov_b32_e32 v3, v32
	v_pk_mul_f32 v[2:3], v[2:3], v[34:35] op_sel_hi:[1,0]
	v_mov_b32_e32 v32, v31
	v_pk_mul_f32 v[4:5], v[32:33], v[34:35] op_sel_hi:[1,0]
	v_and_b32_sdwa v6, v3, v135 dst_sel:DWORD dst_unused:UNUSED_PAD src0_sel:WORD_1 src1_sel:DWORD
	v_and_b32_sdwa v7, v2, v135 dst_sel:DWORD dst_unused:UNUSED_PAD src0_sel:WORD_1 src1_sel:DWORD
	v_add3_u32 v2, v2, v7, s76
	v_add3_u32 v3, v3, v6, s76
	v_and_b32_sdwa v6, v5, v135 dst_sel:DWORD dst_unused:UNUSED_PAD src0_sel:WORD_1 src1_sel:DWORD
	v_and_b32_sdwa v7, v4, v135 dst_sel:DWORD dst_unused:UNUSED_PAD src0_sel:WORD_1 src1_sel:DWORD
	v_add3_u32 v5, v5, v6, s76
	v_add3_u32 v4, v4, v7, s76
	v_and_b32_e32 v5, 0xffff0000, v5
	v_and_b32_e32 v4, 0xffff0000, v4
	v_or_b32_sdwa v3, v5, v3 dst_sel:DWORD dst_unused:UNUSED_PAD src0_sel:DWORD src1_sel:WORD_1
	v_or_b32_sdwa v2, v4, v2 dst_sel:DWORD dst_unused:UNUSED_PAD src0_sel:DWORD src1_sel:WORD_1
	global_store_dwordx2 v[36:37], v[2:3], off offset:1072
	v_mov_b32_e32 v2, v14
	v_mov_b32_e32 v3, v16
	v_pk_mul_f32 v[2:3], v[2:3], v[34:35] op_sel_hi:[1,0]
	v_mov_b32_e32 v16, v15
	v_pk_mul_f32 v[4:5], v[16:17], v[34:35] op_sel_hi:[1,0]
	v_and_b32_sdwa v6, v3, v135 dst_sel:DWORD dst_unused:UNUSED_PAD src0_sel:WORD_1 src1_sel:DWORD
	v_and_b32_sdwa v7, v2, v135 dst_sel:DWORD dst_unused:UNUSED_PAD src0_sel:WORD_1 src1_sel:DWORD
	v_add3_u32 v2, v2, v7, s76
	v_add3_u32 v3, v3, v6, s76
	v_and_b32_sdwa v6, v5, v135 dst_sel:DWORD dst_unused:UNUSED_PAD src0_sel:WORD_1 src1_sel:DWORD
	v_and_b32_sdwa v7, v4, v135 dst_sel:DWORD dst_unused:UNUSED_PAD src0_sel:WORD_1 src1_sel:DWORD
	v_add3_u32 v5, v5, v6, s76
	v_add3_u32 v4, v4, v7, s76
	v_and_b32_e32 v5, 0xffff0000, v5
	v_and_b32_e32 v4, 0xffff0000, v4
	v_or_b32_sdwa v3, v5, v3 dst_sel:DWORD dst_unused:UNUSED_PAD src0_sel:DWORD src1_sel:WORD_1
	v_or_b32_sdwa v2, v4, v2 dst_sel:DWORD dst_unused:UNUSED_PAD src0_sel:DWORD src1_sel:WORD_1
	global_store_dwordx2 v[36:37], v[2:3], off offset:1136
	s_barrier
	s_and_saveexec_b64 s[38:39], s[52:53]
	s_cbranch_execz .LBB0_537
	ds_write_b32 v99, v136
	s_branch .LBB0_537
